# P4 epilogue additionally touches the weight tile's first two K-tiles (one more line per thread)
# baseline (speedup 1.0000x reference)
.LBB0_24:
	ds_read_b128 v[154:157], v138
	ds_read_b128 v[158:161], v139
	ds_read_b128 v[162:165], v140
	ds_read_b128 v[194:197], v141
	ds_read_b128 v[198:201], v142
	ds_read_b128 v[202:205], v143
	ds_read_b128 v[206:209], v144
	ds_read_b128 v[210:213], v145
	s_add_u32 s14, s96, s88
	s_addc_u32 s15, s97, s89
	s_add_u32 s14, s14, 0x4000900
	s_addc_u32 s15, s15, 0
	s_add_u32 s36, s42, s88
	s_addc_u32 s37, s43, s89
	s_cmpk_eq_i32 s88, 0x700
	s_cselect_b32 s27, s87, s15
	s_cselect_b32 s26, s86, s14
	s_cselect_b32 s15, s85, s37
	s_cselect_b32 s14, s84, s36
	v_lshl_add_u64 v[166:167], v[130:131], 0, s[88:89]
	s_add_i32 m0, s94, 0xc000
	ds_read_b128 v[214:217], v137
	ds_read_b128 v[218:221], v137 offset:1024
	ds_read_b128 v[222:225], v137 offset:2048
	ds_read_b128 v[226:229], v137 offset:3072
	ds_read_b128 v[230:233], v137 offset:4096
	ds_read_b128 v[234:237], v137 offset:5120
	ds_read_b128 v[238:241], v137 offset:6144
	ds_read_b128 v[242:245], v137 offset:7168
	global_load_lds_dwordx4 v[166:167], off
	v_lshl_add_u64 v[166:167], v[132:133], 0, s[88:89]
	s_mov_b32 m0, s48
	s_nop 0
	global_load_lds_dwordx4 v[166:167], off
	s_waitcnt vmcnt(8)
	s_waitcnt lgkmcnt(0)
	s_barrier
	s_setprio 1
	s_waitcnt lgkmcnt(0)
	v_mfma_f32_16x16x32_bf16 v[124:127], v[154:157], v[214:217], v[124:127]
	v_mfma_f32_16x16x32_bf16 v[120:123], v[162:165], v[214:217], v[120:123]
	v_mfma_f32_16x16x32_bf16 v[116:119], v[154:157], v[222:225], v[116:119]
	v_mfma_f32_16x16x32_bf16 v[112:115], v[162:165], v[222:225], v[112:115]
	v_mfma_f32_16x16x32_bf16 v[108:111], v[154:157], v[230:233], v[108:111]
	v_mfma_f32_16x16x32_bf16 v[104:107], v[162:165], v[230:233], v[104:107]
	v_mfma_f32_16x16x32_bf16 v[76:79], v[154:157], v[238:241], v[76:79]
	v_mfma_f32_16x16x32_bf16 v[72:75], v[162:165], v[238:241], v[72:75]
	v_mfma_f32_16x16x32_bf16 v[124:127], v[158:161], v[218:221], v[124:127]
	v_mfma_f32_16x16x32_bf16 v[120:123], v[194:197], v[218:221], v[120:123]
	v_mfma_f32_16x16x32_bf16 v[116:119], v[158:161], v[226:229], v[116:119]
	v_mfma_f32_16x16x32_bf16 v[112:115], v[194:197], v[226:229], v[112:115]
	v_mfma_f32_16x16x32_bf16 v[108:111], v[158:161], v[234:237], v[108:111]
	v_mfma_f32_16x16x32_bf16 v[104:107], v[194:197], v[234:237], v[104:107]
	v_mfma_f32_16x16x32_bf16 v[76:79], v[158:161], v[242:245], v[76:79]
	v_mfma_f32_16x16x32_bf16 v[72:75], v[194:197], v[242:245], v[72:75]
	s_setprio 0
	s_setprio 1
	v_mfma_f32_16x16x32_bf16 v[100:103], v[198:201], v[214:217], v[100:103]
	v_mfma_f32_16x16x32_bf16 v[96:99], v[206:209], v[214:217], v[96:99]
	v_mfma_f32_16x16x32_bf16 v[92:95], v[198:201], v[222:225], v[92:95]
	v_mfma_f32_16x16x32_bf16 v[88:91], v[206:209], v[222:225], v[88:91]
	v_mfma_f32_16x16x32_bf16 v[84:87], v[198:201], v[230:233], v[84:87]
	v_mfma_f32_16x16x32_bf16 v[80:83], v[206:209], v[230:233], v[80:83]
	v_mfma_f32_16x16x32_bf16 v[52:55], v[198:201], v[238:241], v[52:55]
	v_mfma_f32_16x16x32_bf16 v[44:47], v[206:209], v[238:241], v[44:47]
	v_mfma_f32_16x16x32_bf16 v[100:103], v[202:205], v[218:221], v[100:103]
	v_mfma_f32_16x16x32_bf16 v[96:99], v[210:213], v[218:221], v[96:99]
	v_mfma_f32_16x16x32_bf16 v[92:95], v[202:205], v[226:229], v[92:95]
	v_mfma_f32_16x16x32_bf16 v[88:91], v[210:213], v[226:229], v[88:91]
	v_mfma_f32_16x16x32_bf16 v[84:87], v[202:205], v[234:237], v[84:87]
	v_mfma_f32_16x16x32_bf16 v[80:83], v[210:213], v[234:237], v[80:83]
	v_mfma_f32_16x16x32_bf16 v[52:55], v[202:205], v[242:245], v[52:55]
	v_mfma_f32_16x16x32_bf16 v[44:47], v[210:213], v[242:245], v[44:47]
	s_setprio 0
	s_barrier
	s_mov_b32 m0, s41
	v_lshl_add_u64 v[166:167], s[14:15], 0, v[168:169]
	s_add_u32 s36, s14, 0x40000
	ds_read_b128 v[214:217], v137 offset:16384
	ds_read_b128 v[218:221], v137 offset:17408
	ds_read_b128 v[222:225], v137 offset:18432
	ds_read_b128 v[226:229], v137 offset:19456
	ds_read_b128 v[230:233], v137 offset:20480
	ds_read_b128 v[234:237], v137 offset:21504
	ds_read_b128 v[238:241], v137 offset:22528
	ds_read_b128 v[242:245], v137 offset:23552
	global_load_lds_dwordx4 v[166:167], off
	v_lshl_add_u64 v[246:247], s[14:15], 0, v[128:129]
	s_mov_b32 m0, s59
	s_addc_u32 s37, s15, 0
	global_load_lds_dwordx4 v[246:247], off
	v_lshl_add_u64 v[248:249], s[36:37], 0, v[168:169]
	s_mov_b32 m0, s95
	v_lshl_add_u64 v[250:251], s[26:27], 0, v[128:129]
	global_load_lds_dwordx4 v[248:249], off
	v_lshl_add_u64 v[248:249], s[36:37], 0, v[128:129]
	s_mov_b32 m0, vcc_lo
	s_nop 0
	global_load_lds_dwordx4 v[248:249], off
	v_lshl_add_u64 v[248:249], s[26:27], 0, v[168:169]
	s_mov_b32 m0, s94
	s_nop 0
	global_load_lds_dwordx4 v[248:249], off
	s_mov_b32 m0, vcc_hi
	s_nop 0
	global_load_lds_dwordx4 v[250:251], off
	s_waitcnt vmcnt(8)
	s_waitcnt lgkmcnt(0)
	s_barrier
	s_setprio 1
	s_waitcnt lgkmcnt(0)
	v_mfma_f32_16x16x32_bf16 v[68:71], v[154:157], v[214:217], v[68:71]
	v_mfma_f32_16x16x32_bf16 v[64:67], v[162:165], v[214:217], v[64:67]
	v_mfma_f32_16x16x32_bf16 v[60:63], v[154:157], v[222:225], v[60:63]
	v_mfma_f32_16x16x32_bf16 v[56:59], v[162:165], v[222:225], v[56:59]
	v_mfma_f32_16x16x32_bf16 v[48:51], v[154:157], v[230:233], v[48:51]
	v_mfma_f32_16x16x32_bf16 v[40:43], v[162:165], v[230:233], v[40:43]
	v_mfma_f32_16x16x32_bf16 v[36:39], v[154:157], v[238:241], v[36:39]
	v_mfma_f32_16x16x32_bf16 v[32:35], v[162:165], v[238:241], v[32:35]
	v_mfma_f32_16x16x32_bf16 v[68:71], v[158:161], v[218:221], v[68:71]
	v_mfma_f32_16x16x32_bf16 v[64:67], v[194:197], v[218:221], v[64:67]
	v_mfma_f32_16x16x32_bf16 v[60:63], v[158:161], v[226:229], v[60:63]
	v_mfma_f32_16x16x32_bf16 v[56:59], v[194:197], v[226:229], v[56:59]
	v_mfma_f32_16x16x32_bf16 v[48:51], v[158:161], v[234:237], v[48:51]
	v_mfma_f32_16x16x32_bf16 v[40:43], v[194:197], v[234:237], v[40:43]
	v_mfma_f32_16x16x32_bf16 v[36:39], v[158:161], v[242:245], v[36:39]
	v_mfma_f32_16x16x32_bf16 v[32:35], v[194:197], v[242:245], v[32:35]
	s_setprio 0
	s_setprio 1
	v_mfma_f32_16x16x32_bf16 v[28:31], v[198:201], v[214:217], v[28:31]
	v_mfma_f32_16x16x32_bf16 v[24:27], v[206:209], v[214:217], v[24:27]
	v_mfma_f32_16x16x32_bf16 v[20:23], v[198:201], v[222:225], v[20:23]
	v_mfma_f32_16x16x32_bf16 v[16:19], v[206:209], v[222:225], v[16:19]
	v_mfma_f32_16x16x32_bf16 v[12:15], v[198:201], v[230:233], v[12:15]
	v_mfma_f32_16x16x32_bf16 v[8:11], v[206:209], v[230:233], v[8:11]
	v_mfma_f32_16x16x32_bf16 v[4:7], v[198:201], v[238:241], v[4:7]
	v_mfma_f32_16x16x32_bf16 v[0:3], v[206:209], v[238:241], v[0:3]
	v_mfma_f32_16x16x32_bf16 v[28:31], v[202:205], v[218:221], v[28:31]
	v_mfma_f32_16x16x32_bf16 v[24:27], v[210:213], v[218:221], v[24:27]
	v_mfma_f32_16x16x32_bf16 v[20:23], v[202:205], v[226:229], v[20:23]
	v_mfma_f32_16x16x32_bf16 v[16:19], v[210:213], v[226:229], v[16:19]
	v_mfma_f32_16x16x32_bf16 v[12:15], v[202:205], v[234:237], v[12:15]
	v_mfma_f32_16x16x32_bf16 v[8:11], v[210:213], v[234:237], v[8:11]
	v_mfma_f32_16x16x32_bf16 v[4:7], v[202:205], v[242:245], v[4:7]
	v_mfma_f32_16x16x32_bf16 v[0:3], v[210:213], v[242:245], v[0:3]
	s_setprio 0
	s_barrier
	ds_read_b128 v[154:157], v146
	ds_read_b128 v[158:161], v147
	ds_read_b128 v[162:165], v148
	ds_read_b128 v[194:197], v149
	ds_read_b128 v[198:201], v150
	ds_read_b128 v[202:205], v151
	ds_read_b128 v[206:209], v152
	ds_read_b128 v[210:213], v153
	s_add_u32 s26, s26, 0x40000
	s_addc_u32 s27, s27, 0
	s_mov_b32 m0, s28
	v_lshl_add_u64 v[180:181], s[26:27], 0, v[168:169]
	ds_read_b128 v[214:217], v137 offset:32768
	ds_read_b128 v[218:221], v137 offset:33792
	ds_read_b128 v[222:225], v137 offset:34816
	ds_read_b128 v[226:229], v137 offset:35840
	ds_read_b128 v[230:233], v137 offset:36864
	ds_read_b128 v[234:237], v137 offset:37888
	ds_read_b128 v[238:241], v137 offset:38912
	ds_read_b128 v[242:245], v137 offset:39936
	global_load_lds_dwordx4 v[180:181], off
	v_lshl_add_u64 v[180:181], s[26:27], 0, v[128:129]
	s_mov_b32 m0, s29
	s_nop 0
	global_load_lds_dwordx4 v[180:181], off
	s_waitcnt vmcnt(8)
	s_waitcnt lgkmcnt(0)
	s_barrier
	s_setprio 1
	s_waitcnt lgkmcnt(0)
	v_mfma_f32_16x16x32_bf16 v[124:127], v[154:157], v[214:217], v[124:127]
	v_mfma_f32_16x16x32_bf16 v[120:123], v[162:165], v[214:217], v[120:123]
	v_mfma_f32_16x16x32_bf16 v[116:119], v[154:157], v[222:225], v[116:119]
	v_mfma_f32_16x16x32_bf16 v[112:115], v[162:165], v[222:225], v[112:115]
	v_mfma_f32_16x16x32_bf16 v[108:111], v[154:157], v[230:233], v[108:111]
	v_mfma_f32_16x16x32_bf16 v[104:107], v[162:165], v[230:233], v[104:107]
	v_mfma_f32_16x16x32_bf16 v[76:79], v[154:157], v[238:241], v[76:79]
	v_mfma_f32_16x16x32_bf16 v[72:75], v[162:165], v[238:241], v[72:75]
	v_mfma_f32_16x16x32_bf16 v[124:127], v[158:161], v[218:221], v[124:127]
	v_mfma_f32_16x16x32_bf16 v[120:123], v[194:197], v[218:221], v[120:123]
	v_mfma_f32_16x16x32_bf16 v[116:119], v[158:161], v[226:229], v[116:119]
	v_mfma_f32_16x16x32_bf16 v[112:115], v[194:197], v[226:229], v[112:115]
	v_mfma_f32_16x16x32_bf16 v[108:111], v[158:161], v[234:237], v[108:111]
	v_mfma_f32_16x16x32_bf16 v[104:107], v[194:197], v[234:237], v[104:107]
	v_mfma_f32_16x16x32_bf16 v[76:79], v[158:161], v[242:245], v[76:79]
	v_mfma_f32_16x16x32_bf16 v[72:75], v[194:197], v[242:245], v[72:75]
	s_setprio 0
	s_setprio 1
	v_mfma_f32_16x16x32_bf16 v[100:103], v[198:201], v[214:217], v[100:103]
	v_mfma_f32_16x16x32_bf16 v[96:99], v[206:209], v[214:217], v[96:99]
	v_mfma_f32_16x16x32_bf16 v[92:95], v[198:201], v[222:225], v[92:95]
	v_mfma_f32_16x16x32_bf16 v[88:91], v[206:209], v[222:225], v[88:91]
	v_mfma_f32_16x16x32_bf16 v[84:87], v[198:201], v[230:233], v[84:87]
	v_mfma_f32_16x16x32_bf16 v[80:83], v[206:209], v[230:233], v[80:83]
	v_mfma_f32_16x16x32_bf16 v[52:55], v[198:201], v[238:241], v[52:55]
	v_mfma_f32_16x16x32_bf16 v[44:47], v[206:209], v[238:241], v[44:47]
	v_mfma_f32_16x16x32_bf16 v[100:103], v[202:205], v[218:221], v[100:103]
	v_mfma_f32_16x16x32_bf16 v[96:99], v[210:213], v[218:221], v[96:99]
	v_mfma_f32_16x16x32_bf16 v[92:95], v[202:205], v[226:229], v[92:95]
	v_mfma_f32_16x16x32_bf16 v[88:91], v[210:213], v[226:229], v[88:91]
	v_mfma_f32_16x16x32_bf16 v[84:87], v[202:205], v[234:237], v[84:87]
	v_mfma_f32_16x16x32_bf16 v[80:83], v[210:213], v[234:237], v[80:83]
	v_mfma_f32_16x16x32_bf16 v[52:55], v[202:205], v[242:245], v[52:55]
	v_mfma_f32_16x16x32_bf16 v[44:47], v[210:213], v[242:245], v[44:47]
	s_setprio 0
	s_barrier
	s_mov_b32 m0, s19
	v_lshl_add_u64 v[166:167], v[166:167], 0, s[34:35]
	s_add_u32 s14, s14, 0x40080
	ds_read_b128 v[214:217], v137 offset:49152
	ds_read_b128 v[218:221], v137 offset:50176
	ds_read_b128 v[222:225], v137 offset:51200
	ds_read_b128 v[226:229], v137 offset:52224
	ds_read_b128 v[230:233], v137 offset:53248
	ds_read_b128 v[234:237], v137 offset:54272
	ds_read_b128 v[238:241], v137 offset:55296
	ds_read_b128 v[242:245], v137 offset:56320
	global_load_lds_dwordx4 v[166:167], off
	v_lshl_add_u64 v[166:167], v[246:247], 0, s[34:35]
	s_mov_b32 m0, s30
	s_addc_u32 s15, s15, 0
	global_load_lds_dwordx4 v[166:167], off
	v_lshl_add_u64 v[166:167], s[14:15], 0, v[168:169]
	s_mov_b32 m0, s63
	s_nop 0
	global_load_lds_dwordx4 v[166:167], off
	v_lshl_add_u64 v[166:167], s[14:15], 0, v[128:129]
	s_mov_b32 m0, s24
	s_nop 0
	global_load_lds_dwordx4 v[166:167], off
	v_lshl_add_u64 v[166:167], v[248:249], 0, s[34:35]
	s_mov_b32 m0, s61
	s_nop 0
	global_load_lds_dwordx4 v[166:167], off
	v_lshl_add_u64 v[166:167], v[250:251], 0, s[34:35]
	s_mov_b32 m0, s62
	s_nop 0
	global_load_lds_dwordx4 v[166:167], off
	s_waitcnt vmcnt(8)
	s_waitcnt lgkmcnt(0)
	s_barrier
	s_setprio 1
	s_waitcnt lgkmcnt(0)
	v_mfma_f32_16x16x32_bf16 v[68:71], v[154:157], v[214:217], v[68:71]
	v_mfma_f32_16x16x32_bf16 v[64:67], v[162:165], v[214:217], v[64:67]
	v_mfma_f32_16x16x32_bf16 v[60:63], v[154:157], v[222:225], v[60:63]
	v_mfma_f32_16x16x32_bf16 v[56:59], v[162:165], v[222:225], v[56:59]
	v_mfma_f32_16x16x32_bf16 v[48:51], v[154:157], v[230:233], v[48:51]
	v_mfma_f32_16x16x32_bf16 v[40:43], v[162:165], v[230:233], v[40:43]
	v_mfma_f32_16x16x32_bf16 v[36:39], v[154:157], v[238:241], v[36:39]
	v_mfma_f32_16x16x32_bf16 v[32:35], v[162:165], v[238:241], v[32:35]
	v_mfma_f32_16x16x32_bf16 v[68:71], v[158:161], v[218:221], v[68:71]
	v_mfma_f32_16x16x32_bf16 v[64:67], v[194:197], v[218:221], v[64:67]
	v_mfma_f32_16x16x32_bf16 v[60:63], v[158:161], v[226:229], v[60:63]
	v_mfma_f32_16x16x32_bf16 v[56:59], v[194:197], v[226:229], v[56:59]
	v_mfma_f32_16x16x32_bf16 v[48:51], v[158:161], v[234:237], v[48:51]
	v_mfma_f32_16x16x32_bf16 v[40:43], v[194:197], v[234:237], v[40:43]
	v_mfma_f32_16x16x32_bf16 v[36:39], v[158:161], v[242:245], v[36:39]
	v_mfma_f32_16x16x32_bf16 v[32:35], v[194:197], v[242:245], v[32:35]
	s_setprio 0
	s_setprio 1
	v_mfma_f32_16x16x32_bf16 v[28:31], v[198:201], v[214:217], v[28:31]
	v_mfma_f32_16x16x32_bf16 v[24:27], v[206:209], v[214:217], v[24:27]
	v_mfma_f32_16x16x32_bf16 v[20:23], v[198:201], v[222:225], v[20:23]
	v_mfma_f32_16x16x32_bf16 v[16:19], v[206:209], v[222:225], v[16:19]
	v_mfma_f32_16x16x32_bf16 v[12:15], v[198:201], v[230:233], v[12:15]
	v_mfma_f32_16x16x32_bf16 v[8:11], v[206:209], v[230:233], v[8:11]
	v_mfma_f32_16x16x32_bf16 v[4:7], v[198:201], v[238:241], v[4:7]
	v_mfma_f32_16x16x32_bf16 v[0:3], v[206:209], v[238:241], v[0:3]
	v_mfma_f32_16x16x32_bf16 v[28:31], v[202:205], v[218:221], v[28:31]
	v_mfma_f32_16x16x32_bf16 v[24:27], v[210:213], v[218:221], v[24:27]
	v_mfma_f32_16x16x32_bf16 v[20:23], v[202:205], v[226:229], v[20:23]
	v_mfma_f32_16x16x32_bf16 v[16:19], v[210:213], v[226:229], v[16:19]
	v_mfma_f32_16x16x32_bf16 v[12:15], v[202:205], v[234:237], v[12:15]
	v_mfma_f32_16x16x32_bf16 v[8:11], v[210:213], v[234:237], v[8:11]
	v_mfma_f32_16x16x32_bf16 v[4:7], v[202:205], v[242:245], v[4:7]
	v_mfma_f32_16x16x32_bf16 v[0:3], v[210:213], v[242:245], v[0:3]
	s_setprio 0
	s_barrier
	s_add_i32 s60, s60, 2
	s_add_u32 s88, s88, 0x100
	s_addc_u32 s89, s89, 0
	s_cmp_lt_u32 s60, 12
	s_cbranch_scc1 .LBB0_24
	ds_read_b128 v[154:157], v138
	ds_read_b128 v[158:161], v139
	ds_read_b128 v[162:165], v140
	ds_read_b128 v[194:197], v141
	ds_read_b128 v[198:201], v142
	ds_read_b128 v[202:205], v143
	ds_read_b128 v[206:209], v144
	ds_read_b128 v[210:213], v145
	s_add_u32 s14, s96, s88
	s_addc_u32 s15, s97, s89
	s_add_u32 s14, s14, 0x4000900
	s_addc_u32 s15, s15, 0
	s_add_u32 s36, s42, s88
	s_addc_u32 s37, s43, s89
	s_cmpk_eq_i32 s88, 0x700
	s_cselect_b32 s27, s87, s15
	s_cselect_b32 s26, s86, s14
	s_cselect_b32 s15, s85, s37
	s_cselect_b32 s14, s84, s36
	v_lshl_add_u64 v[166:167], v[130:131], 0, s[88:89]
	s_add_i32 m0, s94, 0xc000
	ds_read_b128 v[214:217], v137
	ds_read_b128 v[218:221], v137 offset:1024
	ds_read_b128 v[222:225], v137 offset:2048
	ds_read_b128 v[226:229], v137 offset:3072
	ds_read_b128 v[230:233], v137 offset:4096
	ds_read_b128 v[234:237], v137 offset:5120
	ds_read_b128 v[238:241], v137 offset:6144
	ds_read_b128 v[242:245], v137 offset:7168
	global_load_lds_dwordx4 v[166:167], off
	v_lshl_add_u64 v[166:167], v[132:133], 0, s[88:89]
	s_mov_b32 m0, s48
	s_nop 0
	global_load_lds_dwordx4 v[166:167], off
	s_waitcnt vmcnt(8)
	s_waitcnt lgkmcnt(0)
	s_barrier
	s_setprio 1
	s_waitcnt lgkmcnt(0)
	v_mfma_f32_16x16x32_bf16 v[124:127], v[154:157], v[214:217], v[124:127]
	v_mfma_f32_16x16x32_bf16 v[120:123], v[162:165], v[214:217], v[120:123]
	v_mfma_f32_16x16x32_bf16 v[116:119], v[154:157], v[222:225], v[116:119]
	v_mfma_f32_16x16x32_bf16 v[112:115], v[162:165], v[222:225], v[112:115]
	v_mfma_f32_16x16x32_bf16 v[108:111], v[154:157], v[230:233], v[108:111]
	v_mfma_f32_16x16x32_bf16 v[104:107], v[162:165], v[230:233], v[104:107]
	v_mfma_f32_16x16x32_bf16 v[76:79], v[154:157], v[238:241], v[76:79]
	v_mfma_f32_16x16x32_bf16 v[72:75], v[162:165], v[238:241], v[72:75]
	v_mfma_f32_16x16x32_bf16 v[124:127], v[158:161], v[218:221], v[124:127]
	v_mfma_f32_16x16x32_bf16 v[120:123], v[194:197], v[218:221], v[120:123]
	v_mfma_f32_16x16x32_bf16 v[116:119], v[158:161], v[226:229], v[116:119]
	v_mfma_f32_16x16x32_bf16 v[112:115], v[194:197], v[226:229], v[112:115]
	v_mfma_f32_16x16x32_bf16 v[108:111], v[158:161], v[234:237], v[108:111]
	v_mfma_f32_16x16x32_bf16 v[104:107], v[194:197], v[234:237], v[104:107]
	v_mfma_f32_16x16x32_bf16 v[76:79], v[158:161], v[242:245], v[76:79]
	v_mfma_f32_16x16x32_bf16 v[72:75], v[194:197], v[242:245], v[72:75]
	s_setprio 0
	s_setprio 1
	v_mfma_f32_16x16x32_bf16 v[100:103], v[198:201], v[214:217], v[100:103]
	v_mfma_f32_16x16x32_bf16 v[96:99], v[206:209], v[214:217], v[96:99]
	v_mfma_f32_16x16x32_bf16 v[92:95], v[198:201], v[222:225], v[92:95]
	v_mfma_f32_16x16x32_bf16 v[88:91], v[206:209], v[222:225], v[88:91]
	v_mfma_f32_16x16x32_bf16 v[84:87], v[198:201], v[230:233], v[84:87]
	v_mfma_f32_16x16x32_bf16 v[80:83], v[206:209], v[230:233], v[80:83]
	v_mfma_f32_16x16x32_bf16 v[52:55], v[198:201], v[238:241], v[52:55]
	v_mfma_f32_16x16x32_bf16 v[44:47], v[206:209], v[238:241], v[44:47]
	v_mfma_f32_16x16x32_bf16 v[100:103], v[202:205], v[218:221], v[100:103]
	v_mfma_f32_16x16x32_bf16 v[96:99], v[210:213], v[218:221], v[96:99]
	v_mfma_f32_16x16x32_bf16 v[92:95], v[202:205], v[226:229], v[92:95]
	v_mfma_f32_16x16x32_bf16 v[88:91], v[210:213], v[226:229], v[88:91]
	v_mfma_f32_16x16x32_bf16 v[84:87], v[202:205], v[234:237], v[84:87]
	v_mfma_f32_16x16x32_bf16 v[80:83], v[210:213], v[234:237], v[80:83]
	v_mfma_f32_16x16x32_bf16 v[52:55], v[202:205], v[242:245], v[52:55]
	v_mfma_f32_16x16x32_bf16 v[44:47], v[210:213], v[242:245], v[44:47]
	s_setprio 0
	s_barrier
	s_mov_b32 m0, s41
	v_lshl_add_u64 v[166:167], s[14:15], 0, v[168:169]
	s_add_u32 s36, s14, 0x40000
	ds_read_b128 v[214:217], v137 offset:16384
	ds_read_b128 v[218:221], v137 offset:17408
	ds_read_b128 v[222:225], v137 offset:18432
	ds_read_b128 v[226:229], v137 offset:19456
	ds_read_b128 v[230:233], v137 offset:20480
	ds_read_b128 v[234:237], v137 offset:21504
	ds_read_b128 v[238:241], v137 offset:22528
	ds_read_b128 v[242:245], v137 offset:23552
	v_lshl_add_u64 v[246:247], s[14:15], 0, v[128:129]
	s_mov_b32 m0, s59
	s_addc_u32 s37, s15, 0
	v_lshl_add_u64 v[248:249], s[36:37], 0, v[168:169]
	s_mov_b32 m0, s95
	v_lshl_add_u64 v[250:251], s[26:27], 0, v[128:129]
	v_lshl_add_u64 v[248:249], s[36:37], 0, v[128:129]
	s_mov_b32 m0, vcc_lo
	s_nop 0
	v_lshl_add_u64 v[248:249], s[26:27], 0, v[168:169]
	s_mov_b32 m0, s94
	s_nop 0
	s_mov_b32 m0, vcc_hi
	s_nop 0
	s_waitcnt vmcnt(2)
	s_waitcnt lgkmcnt(0)
	s_barrier
	s_setprio 1
	s_waitcnt lgkmcnt(0)
	v_mfma_f32_16x16x32_bf16 v[68:71], v[154:157], v[214:217], v[68:71]
	v_mfma_f32_16x16x32_bf16 v[64:67], v[162:165], v[214:217], v[64:67]
	v_mfma_f32_16x16x32_bf16 v[60:63], v[154:157], v[222:225], v[60:63]
	v_mfma_f32_16x16x32_bf16 v[56:59], v[162:165], v[222:225], v[56:59]
	v_mfma_f32_16x16x32_bf16 v[48:51], v[154:157], v[230:233], v[48:51]
	v_mfma_f32_16x16x32_bf16 v[40:43], v[162:165], v[230:233], v[40:43]
	v_mfma_f32_16x16x32_bf16 v[36:39], v[154:157], v[238:241], v[36:39]
	v_mfma_f32_16x16x32_bf16 v[32:35], v[162:165], v[238:241], v[32:35]
	v_mfma_f32_16x16x32_bf16 v[68:71], v[158:161], v[218:221], v[68:71]
	v_mfma_f32_16x16x32_bf16 v[64:67], v[194:197], v[218:221], v[64:67]
	v_mfma_f32_16x16x32_bf16 v[60:63], v[158:161], v[226:229], v[60:63]
	v_mfma_f32_16x16x32_bf16 v[56:59], v[194:197], v[226:229], v[56:59]
	v_mfma_f32_16x16x32_bf16 v[48:51], v[158:161], v[234:237], v[48:51]
	v_mfma_f32_16x16x32_bf16 v[40:43], v[194:197], v[234:237], v[40:43]
	v_mfma_f32_16x16x32_bf16 v[36:39], v[158:161], v[242:245], v[36:39]
	v_mfma_f32_16x16x32_bf16 v[32:35], v[194:197], v[242:245], v[32:35]
	s_setprio 0
	s_setprio 1
	v_mfma_f32_16x16x32_bf16 v[28:31], v[198:201], v[214:217], v[28:31]
	v_mfma_f32_16x16x32_bf16 v[24:27], v[206:209], v[214:217], v[24:27]
	v_mfma_f32_16x16x32_bf16 v[20:23], v[198:201], v[222:225], v[20:23]
	v_mfma_f32_16x16x32_bf16 v[16:19], v[206:209], v[222:225], v[16:19]
	v_mfma_f32_16x16x32_bf16 v[12:15], v[198:201], v[230:233], v[12:15]
	v_mfma_f32_16x16x32_bf16 v[8:11], v[206:209], v[230:233], v[8:11]
	v_mfma_f32_16x16x32_bf16 v[4:7], v[198:201], v[238:241], v[4:7]
	v_mfma_f32_16x16x32_bf16 v[0:3], v[206:209], v[238:241], v[0:3]
	v_mfma_f32_16x16x32_bf16 v[28:31], v[202:205], v[218:221], v[28:31]
	v_mfma_f32_16x16x32_bf16 v[24:27], v[210:213], v[218:221], v[24:27]
	v_mfma_f32_16x16x32_bf16 v[20:23], v[202:205], v[226:229], v[20:23]
	v_mfma_f32_16x16x32_bf16 v[16:19], v[210:213], v[226:229], v[16:19]
	v_mfma_f32_16x16x32_bf16 v[12:15], v[202:205], v[234:237], v[12:15]
	v_mfma_f32_16x16x32_bf16 v[8:11], v[210:213], v[234:237], v[8:11]
	v_mfma_f32_16x16x32_bf16 v[4:7], v[202:205], v[242:245], v[4:7]
	v_mfma_f32_16x16x32_bf16 v[0:3], v[210:213], v[242:245], v[0:3]
	s_setprio 0
	s_barrier
	ds_read_b128 v[154:157], v146
	ds_read_b128 v[158:161], v147
	ds_read_b128 v[162:165], v148
	ds_read_b128 v[194:197], v149
	ds_read_b128 v[198:201], v150
	ds_read_b128 v[202:205], v151
	ds_read_b128 v[206:209], v152
	ds_read_b128 v[210:213], v153
	s_add_u32 s26, s26, 0x40000
	s_addc_u32 s27, s27, 0
	s_mov_b32 m0, s28
	v_lshl_add_u64 v[180:181], s[26:27], 0, v[168:169]
	ds_read_b128 v[214:217], v137 offset:32768
	ds_read_b128 v[218:221], v137 offset:33792
	ds_read_b128 v[222:225], v137 offset:34816
	ds_read_b128 v[226:229], v137 offset:35840
	ds_read_b128 v[230:233], v137 offset:36864
	ds_read_b128 v[234:237], v137 offset:37888
	ds_read_b128 v[238:241], v137 offset:38912
	ds_read_b128 v[242:245], v137 offset:39936
	v_lshl_add_u64 v[180:181], s[26:27], 0, v[128:129]
	s_mov_b32 m0, s29
	s_nop 0
	s_waitcnt vmcnt(0)
	s_waitcnt lgkmcnt(0)
	s_barrier
	s_setprio 1
	s_waitcnt lgkmcnt(0)
	v_mfma_f32_16x16x32_bf16 v[124:127], v[154:157], v[214:217], v[124:127]
	v_mfma_f32_16x16x32_bf16 v[120:123], v[162:165], v[214:217], v[120:123]
	v_mfma_f32_16x16x32_bf16 v[116:119], v[154:157], v[222:225], v[116:119]
	v_mfma_f32_16x16x32_bf16 v[112:115], v[162:165], v[222:225], v[112:115]
	v_mfma_f32_16x16x32_bf16 v[108:111], v[154:157], v[230:233], v[108:111]
	v_mfma_f32_16x16x32_bf16 v[104:107], v[162:165], v[230:233], v[104:107]
	v_mfma_f32_16x16x32_bf16 v[76:79], v[154:157], v[238:241], v[76:79]
	v_mfma_f32_16x16x32_bf16 v[72:75], v[162:165], v[238:241], v[72:75]
	v_mfma_f32_16x16x32_bf16 v[124:127], v[158:161], v[218:221], v[124:127]
	v_mfma_f32_16x16x32_bf16 v[120:123], v[194:197], v[218:221], v[120:123]
	v_mfma_f32_16x16x32_bf16 v[116:119], v[158:161], v[226:229], v[116:119]
	v_mfma_f32_16x16x32_bf16 v[112:115], v[194:197], v[226:229], v[112:115]
	v_mfma_f32_16x16x32_bf16 v[108:111], v[158:161], v[234:237], v[108:111]
	v_mfma_f32_16x16x32_bf16 v[104:107], v[194:197], v[234:237], v[104:107]
	v_mfma_f32_16x16x32_bf16 v[76:79], v[158:161], v[242:245], v[76:79]
	v_mfma_f32_16x16x32_bf16 v[72:75], v[194:197], v[242:245], v[72:75]
	s_setprio 0
	s_setprio 1
	v_mfma_f32_16x16x32_bf16 v[100:103], v[198:201], v[214:217], v[100:103]
	v_mfma_f32_16x16x32_bf16 v[96:99], v[206:209], v[214:217], v[96:99]
	v_mfma_f32_16x16x32_bf16 v[92:95], v[198:201], v[222:225], v[92:95]
	v_mfma_f32_16x16x32_bf16 v[88:91], v[206:209], v[222:225], v[88:91]
	v_mfma_f32_16x16x32_bf16 v[84:87], v[198:201], v[230:233], v[84:87]
	v_mfma_f32_16x16x32_bf16 v[80:83], v[206:209], v[230:233], v[80:83]
	v_mfma_f32_16x16x32_bf16 v[52:55], v[198:201], v[238:241], v[52:55]
	v_mfma_f32_16x16x32_bf16 v[44:47], v[206:209], v[238:241], v[44:47]
	v_mfma_f32_16x16x32_bf16 v[100:103], v[202:205], v[218:221], v[100:103]
	v_mfma_f32_16x16x32_bf16 v[96:99], v[210:213], v[218:221], v[96:99]
	v_mfma_f32_16x16x32_bf16 v[92:95], v[202:205], v[226:229], v[92:95]
	v_mfma_f32_16x16x32_bf16 v[88:91], v[210:213], v[226:229], v[88:91]
	v_mfma_f32_16x16x32_bf16 v[84:87], v[202:205], v[234:237], v[84:87]
	v_mfma_f32_16x16x32_bf16 v[80:83], v[210:213], v[234:237], v[80:83]
	v_mfma_f32_16x16x32_bf16 v[52:55], v[202:205], v[242:245], v[52:55]
	v_mfma_f32_16x16x32_bf16 v[44:47], v[210:213], v[242:245], v[44:47]
	s_setprio 0
	s_barrier
	s_mov_b32 m0, s19
	v_lshl_add_u64 v[166:167], v[166:167], 0, s[34:35]
	s_add_u32 s14, s14, 0x40080
	ds_read_b128 v[214:217], v137 offset:49152
	ds_read_b128 v[218:221], v137 offset:50176
	ds_read_b128 v[222:225], v137 offset:51200
	ds_read_b128 v[226:229], v137 offset:52224
	ds_read_b128 v[230:233], v137 offset:53248
	ds_read_b128 v[234:237], v137 offset:54272
	ds_read_b128 v[238:241], v137 offset:55296
	ds_read_b128 v[242:245], v137 offset:56320
	v_lshl_add_u64 v[166:167], v[246:247], 0, s[34:35]
	s_mov_b32 m0, s30
	s_addc_u32 s15, s15, 0
	v_lshl_add_u64 v[166:167], s[14:15], 0, v[168:169]
	s_mov_b32 m0, s63
	s_nop 0
	v_lshl_add_u64 v[166:167], s[14:15], 0, v[128:129]
	s_mov_b32 m0, s24
	s_nop 0
	v_lshl_add_u64 v[166:167], v[248:249], 0, s[34:35]
	s_mov_b32 m0, s61
	s_nop 0
	v_lshl_add_u64 v[166:167], v[250:251], 0, s[34:35]
	s_mov_b32 m0, s62
	s_nop 0
	s_waitcnt vmcnt(0)
	s_waitcnt lgkmcnt(0)
	s_barrier
	s_setprio 1
	s_waitcnt lgkmcnt(0)
	v_mfma_f32_16x16x32_bf16 v[68:71], v[154:157], v[214:217], v[68:71]
	v_mfma_f32_16x16x32_bf16 v[64:67], v[162:165], v[214:217], v[64:67]
	v_mfma_f32_16x16x32_bf16 v[60:63], v[154:157], v[222:225], v[60:63]
	v_mfma_f32_16x16x32_bf16 v[56:59], v[162:165], v[222:225], v[56:59]
	v_mfma_f32_16x16x32_bf16 v[48:51], v[154:157], v[230:233], v[48:51]
	v_mfma_f32_16x16x32_bf16 v[40:43], v[162:165], v[230:233], v[40:43]
	v_mfma_f32_16x16x32_bf16 v[36:39], v[154:157], v[238:241], v[36:39]
	v_mfma_f32_16x16x32_bf16 v[32:35], v[162:165], v[238:241], v[32:35]
	v_mfma_f32_16x16x32_bf16 v[68:71], v[158:161], v[218:221], v[68:71]
	v_mfma_f32_16x16x32_bf16 v[64:67], v[194:197], v[218:221], v[64:67]
	v_mfma_f32_16x16x32_bf16 v[60:63], v[158:161], v[226:229], v[60:63]
	v_mfma_f32_16x16x32_bf16 v[56:59], v[194:197], v[226:229], v[56:59]
	v_mfma_f32_16x16x32_bf16 v[48:51], v[158:161], v[234:237], v[48:51]
	v_mfma_f32_16x16x32_bf16 v[40:43], v[194:197], v[234:237], v[40:43]
	v_mfma_f32_16x16x32_bf16 v[36:39], v[158:161], v[242:245], v[36:39]
	v_mfma_f32_16x16x32_bf16 v[32:35], v[194:197], v[242:245], v[32:35]
	s_setprio 0
	s_setprio 1
	v_mfma_f32_16x16x32_bf16 v[28:31], v[198:201], v[214:217], v[28:31]
	v_mfma_f32_16x16x32_bf16 v[24:27], v[206:209], v[214:217], v[24:27]
	v_mfma_f32_16x16x32_bf16 v[20:23], v[198:201], v[222:225], v[20:23]
	v_mfma_f32_16x16x32_bf16 v[16:19], v[206:209], v[222:225], v[16:19]
	v_mfma_f32_16x16x32_bf16 v[12:15], v[198:201], v[230:233], v[12:15]
	v_mfma_f32_16x16x32_bf16 v[8:11], v[206:209], v[230:233], v[8:11]
	v_mfma_f32_16x16x32_bf16 v[4:7], v[198:201], v[238:241], v[4:7]
	v_mfma_f32_16x16x32_bf16 v[0:3], v[206:209], v[238:241], v[0:3]
	v_mfma_f32_16x16x32_bf16 v[28:31], v[202:205], v[218:221], v[28:31]
	v_mfma_f32_16x16x32_bf16 v[24:27], v[210:213], v[218:221], v[24:27]
	v_mfma_f32_16x16x32_bf16 v[20:23], v[202:205], v[226:229], v[20:23]
	v_mfma_f32_16x16x32_bf16 v[16:19], v[210:213], v[226:229], v[16:19]
	v_mfma_f32_16x16x32_bf16 v[12:15], v[202:205], v[234:237], v[12:15]
	v_mfma_f32_16x16x32_bf16 v[8:11], v[210:213], v[234:237], v[8:11]
	v_mfma_f32_16x16x32_bf16 v[4:7], v[202:205], v[242:245], v[4:7]
	v_mfma_f32_16x16x32_bf16 v[0:3], v[210:213], v[242:245], v[0:3]
	s_setprio 0
	s_barrier
	s_add_i32 s60, s60, 2
	s_add_u32 s88, s88, 0x100
	s_addc_u32 s89, s89, 0
	s_cmp_lt_u32 s60, 14
	v_lshrrev_b32_e32 v248, 1, v192
	v_and_b32_e32 v249, 1, v192
	v_lshlrev_b32_e32 v248, 11, v248
	v_lshl_or_b32 v248, v249, 7, v248
	v_add_u32_e32 v248, 0x3f8000, v248
	v_mov_b32_e32 v249, 0
	v_lshl_add_u64 v[248:249], s[86:87], 0, v[248:249]
	v_mov_b32_e32 v247, 0
	v_lshrrev_b32_e32 v246, 1, v192
	v_and_b32_e32 v243, 1, v192
	v_lshlrev_b32_e32 v246, 11, v246
	v_lshl_or_b32 v246, v243, 7, v246
	v_lshl_add_u64 v[246:247], s[84:85], 0, v[246:247]
	s_waitcnt vmcnt(0)
	s_cmpk_gt_u32 s92, 0xff
	s_cbranch_scc1 .LBB0_27
	s_barrier

.LBB0_29:
	s_or_b64 exec, exec, s[14:15]
	v_mov_b32_e32 v114, v192
	s_waitcnt lgkmcnt(0)
	s_barrier
	s_lshl_b32 s26, s40, 7
	v_lshlrev_b32_e32 v80, 3, v114
	v_and_b32_e32 v115, 0x78, v80
	v_or_b32_e32 v112, s26, v115
	v_ashrrev_i32_e32 v113, 31, v112
	s_mov_b64 s[52:53], s[44:45]
	v_readlane_b32 s44, v255, 16
	v_lshlrev_b64 v[92:93], 2, v[112:113]
	v_readlane_b32 s45, v255, 17
	v_lshl_add_u64 v[84:85], s[56:57], 0, v[92:93]
	v_lshl_add_u64 v[88:89], s[52:53], 0, v[92:93]
	v_lshl_add_u64 v[94:95], s[44:45], 0, v[92:93]
	v_lshl_add_u64 v[108:109], s[48:49], 0, v[92:93]
	global_load_dwordx4 v[80:83], v[84:85], off offset:16
	global_load_dwordx4 v[96:99], v[84:85], off
	s_nop 0
	global_load_dwordx4 v[84:87], v[88:89], off offset:16
	global_load_dwordx4 v[100:103], v[88:89], off
	s_nop 0
	global_load_dwordx4 v[88:91], v[94:95], off offset:16
	global_load_dwordx4 v[104:107], v[94:95], off
	s_nop 0
	global_load_dwordx4 v[92:95], v[108:109], off offset:16
	s_nop 0
	global_load_dwordx4 v[108:111], v[108:109], off
	v_ashrrev_i32_e32 v116, 4, v114
	v_lshrrev_b32_e32 v114, 4, v114
	v_bfi_b32 v118, -4, v116, v114
	s_movk_i32 s5, 0x7f
	v_add_u32_e32 v114, s91, v118
	v_cmp_gt_i32_e32 vcc, s5, v118
	s_mov_b32 s5, 0x14000
	v_cmp_gt_i32_e64 s[40:41], s5, v114
	s_movk_i32 s5, 0x410
	v_lshlrev_b32_e32 v116, 2, v115
	v_mul_lo_u32 v117, v118, s5
	s_and_b64 s[28:29], vcc, s[40:41]
	v_add_u32_e32 v120, v116, v117
	v_lshl_add_u32 v119, v115, 2, v117
	s_and_saveexec_b64 s[14:15], s[28:29]
	s_mov_b32 s92, 0
	s_mov_b32 s93, 0x403e0000
	s_cbranch_execz .LBB0_31
	v_cmp_gt_i32_e32 vcc, s33, v114
	ds_read_b128 v[122:125], v120
	ds_read_b128 v[130:133], v120 offset:16
	ds_read_b128 v[136:139], v119 offset:1040
	ds_read_b128 v[140:143], v119 offset:1056
	ds_read_b128 v[144:147], v119 offset:2080
	ds_read_b128 v[148:151], v119 offset:2096
	ds_read_b128 v[152:155], v119 offset:1552
	ds_read_b128 v[156:159], v119 offset:1568
	v_cndmask_b32_e32 v115, v178, v179, vcc
	v_and_b32_e32 v115, v115, v114
	v_cndmask_b32_e32 v121, v175, v176, vcc
	v_cmp_ne_u32_e32 vcc, 0, v115
	v_add_u32_e32 v115, 1, v115
	s_mov_b32 s24, 0xc0135761
	s_waitcnt lgkmcnt(6)
	v_cndmask_b32_e32 v127, 0, v133, vcc
	v_cndmask_b32_e32 v126, 0, v132, vcc
	v_cndmask_b32_e32 v131, 0, v131, vcc
	v_cndmask_b32_e32 v130, 0, v130, vcc
	v_cndmask_b32_e32 v125, 0, v125, vcc
	v_cndmask_b32_e32 v124, 0, v124, vcc
	v_cndmask_b32_e32 v123, 0, v123, vcc
	v_cndmask_b32_e32 v122, 0, v122, vcc
	v_cmp_lt_u32_e32 vcc, v115, v121
	v_ashrrev_i32_e32 v115, 31, v114
	v_lshlrev_b64 v[114:115], 13, v[114:115]
	s_waitcnt lgkmcnt(3)
	v_cndmask_b32_e32 v145, 0, v145, vcc
	v_cndmask_b32_e32 v144, 0, v144, vcc
	s_waitcnt vmcnt(0)
	global_load_dword v250, v[248:249], off
	global_load_dword v251, v[246:247], off
	v_pk_fma_f32 v[144:145], v[104:105], v[144:145], v[108:109]
	v_cndmask_b32_e32 v147, 0, v147, vcc
	v_pk_fma_f32 v[136:137], v[100:101], v[136:137], v[144:145]
	v_mov_b64_e32 v[144:145], s[24:25]
	v_pk_fma_f32 v[122:123], v[96:97], v[122:123], v[136:137]
	s_mov_b32 s24, 0x3dd2d3e8
	v_pk_mul_f32 v[136:137], v[122:123], v[122:123]
	v_cndmask_b32_e32 v146, 0, v146, vcc
	v_pk_fma_f32 v[136:137], v[136:137], s[24:25], v[144:145] op_sel_hi:[1,0,0] neg_lo:[1,0,0] neg_hi:[1,0,0]
	s_waitcnt lgkmcnt(2)
	v_cndmask_b32_e32 v133, 0, v151, vcc
	v_pk_mul_f32 v[136:137], v[122:123], v[136:137]
	v_cndmask_b32_e32 v132, 0, v150, vcc
	v_exp_f32_e32 v136, v136
	v_exp_f32_e32 v137, v137
	v_cndmask_b32_e32 v149, 0, v149, vcc
	v_cndmask_b32_e32 v148, 0, v148, vcc
	v_pk_fma_f32 v[132:133], v[90:91], v[132:133], v[94:95]
	v_pk_add_f32 v[136:137], v[136:137], 1.0 op_sel_hi:[1,0]
	v_pk_fma_f32 v[132:133], v[86:87], v[142:143], v[132:133]
	v_rcp_f32_e32 v136, v136
	v_rcp_f32_e32 v137, v137
	v_pk_fma_f32 v[126:127], v[82:83], v[126:127], v[132:133]
	v_lshl_add_u64 v[114:115], s[46:47], 0, v[114:115]
	v_pk_mul_f32 v[132:133], v[126:127], v[126:127]
	v_pk_mul_f32 v[122:123], v[122:123], v[136:137]
	v_pk_fma_f32 v[136:137], v[106:107], v[146:147], v[110:111]
	v_pk_fma_f32 v[132:133], v[132:133], s[24:25], v[144:145] op_sel_hi:[1,0,0] neg_lo:[1,0,0] neg_hi:[1,0,0]
	v_pk_fma_f32 v[136:137], v[102:103], v[138:139], v[136:137]
	v_pk_mul_f32 v[132:133], v[126:127], v[132:133]
	v_pk_fma_f32 v[124:125], v[98:99], v[124:125], v[136:137]
	v_exp_f32_e32 v132, v132
	v_pk_mul_f32 v[136:137], v[124:125], v[124:125]
	v_exp_f32_e32 v133, v133
	v_pk_fma_f32 v[136:137], v[136:137], s[24:25], v[144:145] op_sel_hi:[1,0,0] neg_lo:[1,0,0] neg_hi:[1,0,0]
	s_waitcnt lgkmcnt(1)
	v_pk_mul_f32 v[122:123], v[152:153], v[122:123]
	v_pk_mul_f32 v[136:137], v[124:125], v[136:137]
	v_pk_add_f32 v[132:133], v[132:133], 1.0 op_sel_hi:[1,0]
	v_exp_f32_e32 v136, v136
	v_exp_f32_e32 v137, v137
	v_rcp_f32_e32 v132, v132
	v_rcp_f32_e32 v133, v133
	v_cvt_pk_bf16_f32 v122, v122, v123
	v_pk_add_f32 v[136:137], v[136:137], 1.0 op_sel_hi:[1,0]
	v_lshl_add_u64 v[114:115], v[112:113], 1, v[114:115]
	v_rcp_f32_e32 v136, v136
	v_rcp_f32_e32 v137, v137
	v_pk_mul_f32 v[126:127], v[126:127], v[132:133]
	v_pk_mul_f32 v[124:125], v[124:125], v[136:137]
	v_pk_fma_f32 v[136:137], v[88:89], v[148:149], v[92:93]
	v_pk_mul_f32 v[124:125], v[154:155], v[124:125]
	v_pk_fma_f32 v[136:137], v[84:85], v[140:141], v[136:137]
	s_waitcnt lgkmcnt(0)
	v_pk_mul_f32 v[126:127], v[158:159], v[126:127]
	v_pk_fma_f32 v[130:131], v[80:81], v[130:131], v[136:137]
	v_cvt_pk_bf16_f32 v123, v124, v125
	v_pk_mul_f32 v[136:137], v[130:131], v[130:131]
	v_cvt_pk_bf16_f32 v125, v126, v127
	v_pk_fma_f32 v[136:137], v[136:137], s[24:25], v[144:145] op_sel_hi:[1,0,0] neg_lo:[1,0,0] neg_hi:[1,0,0]
	s_nop 0
	v_pk_mul_f32 v[136:137], v[130:131], v[136:137]
	s_nop 0
	v_exp_f32_e32 v136, v136
	v_exp_f32_e32 v137, v137
	s_nop 0
	v_pk_add_f32 v[136:137], v[136:137], 1.0 op_sel_hi:[1,0]
	s_nop 0
	v_rcp_f32_e32 v136, v136
	v_rcp_f32_e32 v137, v137
	s_nop 0
	v_pk_mul_f32 v[130:131], v[130:131], v[136:137]
	s_nop 0
	v_pk_mul_f32 v[130:131], v[156:157], v[130:131]
	s_nop 0
	v_cvt_pk_bf16_f32 v124, v130, v131
	global_store_dwordx4 v[114:115], v[122:125], off

.Lp4_skip_b0:
	s_waitcnt vmcnt(0)
	s_branch .LBB0_41
	s_nop 0
	s_nop 0
	s_nop 0
	s_nop 0
	s_nop 0
	s_nop 0
	s_nop 0
	s_nop 0
	s_nop 0
	s_nop 0
	s_nop 0
	s_nop 0
	s_nop 0
	s_nop 0
